# v050 + layer-1 weight conversion deferred from P0 into the idle blocks of P5's last GEMM round (R=0: GEMV blocks convert nothing in P0)
# baseline (speedup 1.0000x reference)
.LBB0_17:
	s_mov_b32 s94, 0
	s_mov_b32 s95, 0
	s_movk_i32 s96, 0x2c0
	s_movk_i32 s97, 0x420
	s_movk_i32 s93, 0x500
	s_sub_i32 s92, 0xff, s2
	s_movk_i32 s90, 0x70
	s_cmpk_gt_i32 s92, 0x6f
	s_cbranch_scc1 .LBB0_52
.Lmy_cv_setup:
	s_add_u32 s14, s38, 0x4900000
	s_addc_u32 s15, s39, 0
	s_add_u32 s16, s38, 0x4700000
	s_addc_u32 s17, s39, 0
	s_load_dwordx2 s[10:11], s[0:1], 0xa0
	s_load_dwordx2 s[12:13], s[0:1], 0x90
	s_load_dwordx4 s[4:7], s[0:1], 0x58
	s_add_u32 s18, s38, 0x4200000
	s_addc_u32 s19, s39, 0
	s_add_u32 s20, s38, 0x4f00000
	s_addc_u32 s21, s39, 0
	s_add_u32 s69, s38, 0x2c00000
	s_addc_u32 s70, s39, 0
	s_movk_i32 s71, 0x800
	v_mov_b32_e32 v3, 0
	s_movk_i32 s72, 0x204
	s_movk_i32 s73, 0x3ff
	s_movk_i32 s74, 0x200
	s_movk_i32 s75, 0xb00
	v_mov_b32_e32 v4, 0x80
	s_branch .Lmy_cv_head

.LBB0_20:
	v_lshlrev_b32_e32 v2, 5, v5
	v_and_b32_e32 v5, 0x60, v2
	v_ashrrev_i32_e32 v2, 31, v7
	v_mul_lo_u32 v10, s25, v7
	v_mul_lo_u32 v2, s24, v2
	v_mad_u64_u32 v[8:9], s[24:25], s24, v7, 0
	v_add3_u32 v9, v9, v2, v10
	v_lshlrev_b32_e32 v2, 1, v5
	v_lshlrev_b32_e32 v6, 2, v6
	v_mul_u32_u24_e32 v5, 0x204, v5
	v_lshl_add_u64 v[8:9], v[8:9], 1, s[22:23]
	s_ashr_i32 s29, s28, 31
	v_add3_u32 v5, 0, v6, v5
	v_lshl_add_u64 v[8:9], s[28:29], 1, v[8:9]
	v_add_u32_e32 v10, 0x400, v5
	ds_read2_b32 v[6:7], v5 offset1:129
	ds_read2_b32 v[10:11], v10 offset0:2 offset1:131
	v_add_u32_e32 v12, 0x800, v5
	v_add_u32_e32 v14, 0xc00, v5
	v_lshl_add_u64 v[16:17], v[8:9], 0, v[2:3]
	v_add_u32_e32 v2, 0x1000, v5
	ds_read2_b32 v[12:13], v12 offset0:4 offset1:133
	ds_read2_b32 v[14:15], v14 offset0:6 offset1:135
	s_waitcnt lgkmcnt(3)
	v_cvt_pk_bf16_f32 v6, v6, v7
	s_waitcnt lgkmcnt(2)
	v_cvt_pk_bf16_f32 v7, v10, v11
	s_waitcnt lgkmcnt(1)
	v_cvt_pk_bf16_f32 v8, v12, v13
	s_waitcnt lgkmcnt(0)
	v_cvt_pk_bf16_f32 v9, v14, v15
	ds_read2_b32 v[10:11], v2 offset0:8 offset1:137
	v_add_u32_e32 v2, 0x1400, v5
	ds_read2_b32 v[12:13], v2 offset0:10 offset1:139
	v_add_u32_e32 v2, 0x1800, v5
	ds_read2_b32 v[14:15], v2 offset0:12 offset1:141
	v_add_u32_e32 v2, 0x1c00, v5
	ds_read2_b32 v[18:19], v2 offset0:14 offset1:143
	v_add_u32_e32 v2, 0x2000, v5
	global_store_dwordx4 v[16:17], v[6:9], off
	s_waitcnt lgkmcnt(3)
	v_cvt_pk_bf16_f32 v6, v10, v11
	s_waitcnt lgkmcnt(2)
	v_cvt_pk_bf16_f32 v7, v12, v13
	s_waitcnt lgkmcnt(1)
	v_cvt_pk_bf16_f32 v8, v14, v15
	s_waitcnt lgkmcnt(0)
	v_cvt_pk_bf16_f32 v9, v18, v19
	ds_read2_b32 v[10:11], v2 offset0:16 offset1:145
	v_add_u32_e32 v2, 0x2400, v5
	ds_read2_b32 v[12:13], v2 offset0:18 offset1:147
	v_add_u32_e32 v2, 0x2800, v5
	ds_read2_b32 v[14:15], v2 offset0:20 offset1:149
	v_add_u32_e32 v2, 0x2c00, v5
	ds_read2_b32 v[18:19], v2 offset0:22 offset1:151
	v_add_u32_e32 v2, 0x3000, v5
	global_store_dwordx4 v[16:17], v[6:9], off offset:16
	s_waitcnt lgkmcnt(3)
	s_nop 0
	v_cvt_pk_bf16_f32 v6, v10, v11
	s_waitcnt lgkmcnt(2)
	v_cvt_pk_bf16_f32 v7, v12, v13
	s_waitcnt lgkmcnt(1)
	v_cvt_pk_bf16_f32 v8, v14, v15
	s_waitcnt lgkmcnt(0)
	v_cvt_pk_bf16_f32 v9, v18, v19
	ds_read2_b32 v[10:11], v2 offset0:24 offset1:153
	v_add_u32_e32 v2, 0x3400, v5
	ds_read2_b32 v[12:13], v2 offset0:26 offset1:155
	v_add_u32_e32 v2, 0x3800, v5
	ds_read2_b32 v[14:15], v2 offset0:28 offset1:157
	v_add_u32_e32 v2, 0x3c00, v5
	ds_read2_b32 v[18:19], v2 offset0:30 offset1:159
	global_store_dwordx4 v[16:17], v[6:9], off offset:32
	s_waitcnt lgkmcnt(3)
	s_nop 0
	v_cvt_pk_bf16_f32 v6, v10, v11
	s_waitcnt lgkmcnt(2)
	v_cvt_pk_bf16_f32 v7, v12, v13
	s_waitcnt lgkmcnt(1)
	v_cvt_pk_bf16_f32 v8, v14, v15
	s_waitcnt lgkmcnt(0)
	v_cvt_pk_bf16_f32 v9, v18, v19
	global_store_dwordx4 v[16:17], v[6:9], off offset:48
	s_barrier
	s_add_i32 s92, s92, s90
	s_cmp_lt_i32 s92, s93
	s_cbranch_scc1 .Lmy_cv_head
	s_cmp_eq_u32 s94, 0
	s_cbranch_scc1 .LBB0_52
	s_branch .Lmy_cv_ret
.Lmy_cv_head:
	s_cmpk_lt_i32 s92, 0x2c0
	s_cselect_b32 s68, s95, s96
	s_cmpk_lt_i32 s92, 0x420
	s_cselect_b32 s68, s68, s97
	s_add_i32 s68, s68, s92

.LBB0_560:
	s_waitcnt vmcnt(0)
	s_barrier
	s_cmp_lt_u32 s2, 32
	s_cbranch_scc1 .LBB0_561
	s_mov_b64 s[86:87], s[52:53]
	s_mov_b64 s[88:89], s[54:55]
	s_mov_b64 s[98:99], s[70:71]
	s_mov_b32 s94, 1
	s_movk_i32 s95, 0x2c0
	s_movk_i32 s96, 0x420
	s_movk_i32 s97, 0x500
	s_movk_i32 s93, 0x520
	s_movk_i32 s90, 0xe0
	s_sub_i32 s92, s2, 32
	s_branch .Lmy_cv_setup
.Lmy_cv_ret:
	s_mov_b64 s[52:53], s[86:87]
	s_mov_b64 s[54:55], s[88:89]
	s_mov_b64 s[70:71], s[98:99]
